# gate|up phase: units after the first round taken in ascending tile order (neighbouring workgroups share B tiles)
# baseline (speedup 1.0000x reference)
.LBB11_2564:
	s_add_i32 s60, s60, 1
	s_lshl_b64 s[0:1], s[60:61], 4
	s_add_u32 s22, s0, s33
	s_addc_u32 s23, s1, s93
	v_cmp_gt_i64_e32 vcc, s[22:23], v[188:189]
	v_cmp_lt_i64_e64 s[12:13], s[22:23], v[186:187]
	s_mov_b32 s8, -1
	s_cbranch_vccnz .LBB11_2566
	s_sub_i32 s0, s22, 16
	s_mul_hi_u32 s1, s0, 0x1c71c71d
	s_lshl_b32 s1, s1, 1
	s_add_i32 s0, s0, s1
	s_add_i32 s0, s0, 2
	s_mul_hi_i32 s1, s0, 0x2e8ba2e9
	s_lshr_b32 s8, s1, 31
	s_ashr_i32 s1, s1, 5
	s_add_i32 s1, s1, s8
	s_lshl_b32 s8, s1, 3
	s_sub_i32 s9, 4, s8
	s_min_i32 s9, s9, 8
	s_abs_i32 s22, s9
	v_cvt_f32_u32_e32 v2, s22
	s_sub_i32 s24, 0, s22
	s_mulk_i32 s1, 0xb0
	s_sub_i32 s0, s0, s1
	v_rcp_iflag_f32_e32 v2, v2
	s_abs_i32 s1, s0
	s_xor_b32 s23, s0, s9
	s_ashr_i32 s23, s23, 31
	v_mul_f32_e32 v2, 0x4f7ffffe, v2
	v_cvt_u32_f32_e32 v2, v2
	s_nop 0
	v_readfirstlane_b32 s25, v2
	s_mul_i32 s24, s24, s25
	s_mul_hi_u32 s24, s25, s24
	s_add_i32 s25, s25, s24
	s_mul_hi_u32 s24, s1, s25
	s_mul_i32 s25, s24, s22
	s_sub_i32 s1, s1, s25
	s_add_i32 s30, s24, 1
	s_sub_i32 s25, s1, s22
	s_cmp_ge_u32 s1, s22
	s_cselect_b32 s24, s30, s24
	s_cselect_b32 s1, s25, s1
	s_add_i32 s25, s24, 1
	s_cmp_ge_u32 s1, s22
	s_cselect_b32 s1, s25, s24
	s_xor_b32 s1, s1, s23
	s_sub_i32 s43, s1, s23
	s_mul_i32 s1, s43, s9
	s_sub_i32 s0, s0, s1
	s_add_i32 s0, s0, s92
	s_add_i32 s8, s0, s8
	s_lshl_b32 s45, s8, 19
	s_lshl_b32 s44, s43, 19
	s_mov_b32 s46, s8
